# nt hint also on the P9/P10 dwordx4 global loads (residual stream)
# speedup vs baseline: 1.0130x; 1.0079x over previous
.LBB0_859:
	s_mov_b32 s4, 0x2e8ba2e9
	v_mul_hi_i32 v0, v26, s4
	v_lshrrev_b32_e32 v1, 31, v0
	v_ashrrev_i32_e32 v0, 6, v0
	v_add_u32_e32 v6, v0, v1
	v_mul_i32_i24_e32 v0, 0x160, v6
	v_lshlrev_b32_e32 v0, 3, v0
	v_sub_u32_e32 v20, v27, v0
	v_mul_i32_i24_e32 v0, 3, v6
	v_ashrrev_i32_e32 v21, 31, v20
	v_mad_i64_i32 v[0:1], s[4:5], v0, s8, v[16:17]
	v_lshlrev_b64 v[2:3], 2, v[20:21]
	v_lshl_add_u64 v[0:1], v[0:1], 0, v[2:3]
	v_add_co_u32_e32 v4, vcc, 0x5000, v0
	v_ashrrev_i32_e32 v7, 1, v6
	s_nop 0
	v_addc_co_u32_e32 v5, vcc, 0, v1, vcc
	global_load_dwordx4 v[8:11], v[0:1], off nt
	global_load_dwordx4 v[12:15], v[4:5], off offset:2048 nt
	v_bfe_i32 v4, v6, 0, 1
	s_mov_b32 s4, 0x6050400
	v_perm_b32 v30, v7, v4, s4
	s_mov_b32 s4, 0x8000
	v_and_b32_e32 v5, 1, v6
	v_cmp_gt_i32_e32 vcc, s4, v30
	v_and_b32_e32 v18, 0x5800, v4
	s_nop 0
	v_cndmask_b32_e32 v22, v28, v29, vcc
	v_cmp_eq_u32_e32 vcc, 0, v5
	v_and_b32_e32 v23, v22, v30
	v_and_b32_e32 v4, v4, v22
	v_cndmask_b32_e64 v5, 1, -1, vcc
	v_cmp_ne_u32_e64 s[40:41], v23, v4
	v_add_lshl_u32 v4, v5, v7, 1
	v_bitop3_b32 v4, v4, 1, v6 bitop3:0x34
	v_lshl_add_u32 v4, v4, 1, v4
	v_mad_i64_i32 v[4:5], s[4:5], v4, s8, v[16:17]
	v_lshl_add_u64 v[4:5], v[4:5], 0, v[2:3]
	s_mov_b64 s[4:5], 0x2c00
	v_lshl_add_u64 v[22:23], v[4:5], 0, s[4:5]
	v_readlane_b32 s4, v254, 0
	v_readlane_b32 s5, v254, 1
	s_load_dwordx2 s[4:5], s[4:5], 0x60
	s_waitcnt lgkmcnt(0)
	v_lshl_add_u64 v[4:5], s[4:5], 0, v[18:19]
	v_lshl_add_u64 v[24:25], v[4:5], 0, v[2:3]
	s_and_saveexec_b64 s[4:5], s[40:41]
	s_cbranch_execz .LBB0_861
	global_load_dwordx4 v[2:5], v[24:25], off nt
	global_load_dwordx4 v[32:35], v[22:23], off nt
	s_waitcnt vmcnt(0)
	v_pk_fma_f32 v[10:11], v[4:5], v[34:35], v[10:11]
	v_pk_fma_f32 v[8:9], v[2:3], v[32:33], v[8:9]
.LBB0_861:
	s_or_b64 exec, exec, s[4:5]
	v_add_co_u32_e32 v2, vcc, 0x5000, v0
	s_nop 1
	v_addc_co_u32_e32 v3, vcc, 0, v1, vcc
	global_load_dwordx4 v[4:7], v[0:1], off offset:16 nt
	s_nop 0
	global_load_dwordx4 v[0:3], v[2:3], off offset:2064 nt
	s_and_saveexec_b64 s[4:5], s[40:41]
	s_cbranch_execz .LBB0_858
	global_load_dwordx4 v[32:35], v[24:25], off offset:16 nt
	s_nop 0
	global_load_dwordx4 v[22:25], v[22:23], off offset:16 nt
	s_waitcnt vmcnt(0)
	v_pk_fma_f32 v[6:7], v[34:35], v[24:25], v[6:7]
	v_pk_fma_f32 v[4:5], v[32:33], v[22:23], v[4:5]
	s_branch .LBB0_858

.LBB0_958:
	s_lshl_b32 s52, s57, 8
	v_add_u32_e32 v168, s52, v179
	v_lshl_or_b32 v170, s12, 8, v181
	v_ashrrev_i32_e32 v171, 31, v170
	v_ashrrev_i32_e32 v169, 31, v168
	v_lshl_add_u64 v[128:129], v[170:171], 1, s[96:97]
	v_lshlrev_b64 v[130:131], 11, v[168:169]
	v_lshl_add_u64 v[172:173], v[128:129], 0, v[130:131]
	v_or_b32_e32 v130, 16, v168
	v_ashrrev_i32_e32 v131, 31, v130
	v_lshlrev_b64 v[130:131], 11, v[130:131]
	v_mov_b32_e32 v174, v214
	v_lshl_add_u64 v[130:131], v[128:129], 0, v[130:131]
	global_load_dwordx4 v[202:205], v[172:173], off nt
	global_load_dwordx4 v[206:209], v[172:173], off offset:256 nt
	global_load_dwordx4 v[148:151], v[130:131], off nt
	global_load_dwordx4 v[144:147], v[130:131], off offset:256 nt
	v_or_b32_e32 v130, 32, v168
	v_ashrrev_i32_e32 v131, 31, v130
	v_lshlrev_b64 v[130:131], 11, v[130:131]
	v_lshl_add_u64 v[130:131], v[128:129], 0, v[130:131]
	global_load_dwordx4 v[140:143], v[130:131], off nt
	global_load_dwordx4 v[136:139], v[130:131], off offset:256 nt
	v_or_b32_e32 v130, 48, v168
	v_ashrrev_i32_e32 v131, 31, v130
	v_lshlrev_b64 v[130:131], 11, v[130:131]
	v_lshl_add_u64 v[128:129], v[128:129], 0, v[130:131]
	global_load_dwordx4 v[132:135], v[128:129], off nt
	s_nop 0
	global_load_dwordx4 v[128:131], v[128:129], off offset:256 nt
	s_mov_b64 s[14:15], 0x40000
	v_lshl_add_u64 v[252:253], v[172:173], 0, s[14:15]
	global_load_dwordx4 v[216:219], v[252:253], off nt
	global_load_dwordx4 v[220:223], v[252:253], off offset:256 nt
	s_mov_b64 s[14:15], 0x8000
	v_lshl_add_u64 v[252:253], v[252:253], 0, s[14:15]
	global_load_dwordx4 v[224:227], v[252:253], off nt
	global_load_dwordx4 v[228:231], v[252:253], off offset:256 nt
	v_lshl_add_u64 v[252:253], v[252:253], 0, s[14:15]
	global_load_dwordx4 v[232:235], v[252:253], off nt
	global_load_dwordx4 v[244:247], v[252:253], off offset:256 nt
	v_lshl_add_u64 v[252:253], v[252:253], 0, s[14:15]
	global_load_dwordx4 v[248:251], v[252:253], off nt
	v_and_b32_e32 v176, 64, v215
	v_xor_b32_e32 v175, 16, v215
	v_add_u32_e32 v176, 64, v176
	v_cmp_lt_i32_e32 vcc, v175, v176
	v_xor_b32_e32 v177, 32, v215
	s_nop 0
	v_cndmask_b32_e32 v175, v215, v175, vcc
	v_cmp_lt_i32_e32 vcc, v177, v176
	v_lshlrev_b32_e32 v175, 2, v175
	s_nop 0
	v_cndmask_b32_e32 v176, v215, v177, vcc
	v_lshlrev_b32_e32 v176, 2, v176
	s_waitcnt vmcnt(7)
	v_lshlrev_b32_e32 v210, 16, v202
	v_and_b32_e32 v211, 0xffff0000, v202
	v_lshlrev_b32_e32 v202, 16, v203
	v_and_b32_e32 v203, 0xffff0000, v203
	v_pk_add_f32 v[126:127], v[126:127], v[202:203]
	v_pk_add_f32 v[124:125], v[124:125], v[210:211]
	v_lshlrev_b32_e32 v212, 16, v204
	v_and_b32_e32 v213, 0xffff0000, v204
	v_mul_f32_e32 v177, v125, v125
	v_mul_f32_e32 v202, v127, v127
	v_pk_add_f32 v[120:121], v[120:121], v[212:213]
	v_fmac_f32_e32 v177, v124, v124
	v_fmac_f32_e32 v202, v126, v126
	v_lshlrev_b32_e32 v204, 16, v205
	v_and_b32_e32 v205, 0xffff0000, v205
	v_add_f32_e32 v177, v177, v202
	v_mul_f32_e32 v202, v121, v121
	v_pk_add_f32 v[122:123], v[122:123], v[204:205]
	v_fmac_f32_e32 v202, v120, v120
	v_add_f32_e32 v177, v202, v177
	v_mul_f32_e32 v202, v123, v123
	v_fmac_f32_e32 v202, v122, v122
	v_add_f32_e32 v177, v202, v177
	v_lshlrev_b32_e32 v202, 16, v206
	v_and_b32_e32 v203, 0xffff0000, v206
	v_lshlrev_b32_e32 v204, 16, v207
	v_and_b32_e32 v205, 0xffff0000, v207
	v_pk_add_f32 v[118:119], v[118:119], v[204:205]
	v_pk_add_f32 v[116:117], v[116:117], v[202:203]
	v_lshlrev_b32_e32 v206, 16, v208
	v_and_b32_e32 v207, 0xffff0000, v208
	v_mul_f32_e32 v202, v117, v117
	v_mul_f32_e32 v203, v119, v119
	v_pk_add_f32 v[112:113], v[112:113], v[206:207]
	v_fmac_f32_e32 v202, v116, v116
	v_fmac_f32_e32 v203, v118, v118
	v_lshlrev_b32_e32 v208, 16, v209
	v_and_b32_e32 v209, 0xffff0000, v209
	v_add_f32_e32 v202, v202, v203
	v_mul_f32_e32 v203, v113, v113
	v_pk_add_f32 v[114:115], v[114:115], v[208:209]
	v_fmac_f32_e32 v203, v112, v112
	v_add_f32_e32 v202, v203, v202
	v_mul_f32_e32 v203, v115, v115
	v_fmac_f32_e32 v203, v114, v114
	v_add_f32_e32 v202, v203, v202
	v_add_f32_e32 v177, v177, v202
	ds_bpermute_b32 v202, v175, v177
	s_waitcnt lgkmcnt(0)
	v_add_f32_e32 v177, v177, v202
	ds_bpermute_b32 v202, v176, v177
	s_and_saveexec_b64 s[14:15], s[0:1]
	s_cbranch_execz .LBB0_960
	s_waitcnt lgkmcnt(0)
	v_add_f32_e32 v177, v177, v202
	ds_write_b32 v201, v177

.LBB0_966:
	s_or_b64 exec, exec, s[14:15]
	v_add_co_u32_e32 v66, vcc, 0x40000, v172
	s_mov_b64 s[14:15], 0x40000
	s_nop 0
	v_addc_co_u32_e32 v67, vcc, 0, v173, vcc
	s_waitcnt lgkmcnt(0)
	v_lshl_add_u64 v[64:65], v[172:173], 0, s[14:15]
	s_waitcnt vmcnt(0)
	v_mov_b64_e32 v[202:203], v[216:217]
	v_mov_b64_e32 v[204:205], v[218:219]
	v_mov_b64_e32 v[206:207], v[220:221]
	v_mov_b64_e32 v[208:209], v[222:223]
	v_add_co_u32_e32 v66, vcc, 0x48000, v172
	s_mov_b64 s[14:15], 0x48000
	s_nop 0
	v_addc_co_u32_e32 v67, vcc, 0, v173, vcc
	v_lshl_add_u64 v[64:65], v[172:173], 0, s[14:15]
	v_mov_b64_e32 v[84:85], v[224:225]
	v_mov_b64_e32 v[86:87], v[226:227]
	v_mov_b64_e32 v[80:81], v[228:229]
	v_mov_b64_e32 v[82:83], v[230:231]
	v_add_co_u32_e32 v66, vcc, 0x50000, v172
	s_mov_b64 s[14:15], 0x50000
	s_nop 0
	v_addc_co_u32_e32 v67, vcc, 0, v173, vcc
	v_lshl_add_u64 v[64:65], v[172:173], 0, s[14:15]
	v_mov_b64_e32 v[76:77], v[232:233]
	v_mov_b64_e32 v[78:79], v[234:235]
	v_mov_b64_e32 v[72:73], v[244:245]
	v_mov_b64_e32 v[74:75], v[246:247]
	s_mov_b64 s[14:15], 0x58000
	v_add_co_u32_e32 v66, vcc, 0x58000, v172
	v_lshl_add_u64 v[64:65], v[172:173], 0, s[14:15]
	s_nop 0
	v_addc_co_u32_e32 v67, vcc, 0, v173, vcc
	v_mov_b64_e32 v[68:69], v[248:249]
	v_mov_b64_e32 v[70:71], v[250:251]
	s_nop 0
	global_load_dwordx4 v[64:67], v[64:65], off offset:256 nt
	s_waitcnt vmcnt(7)
	v_lshlrev_b32_e32 v172, 16, v202
	v_and_b32_e32 v173, 0xffff0000, v202
	v_lshlrev_b32_e32 v202, 16, v203
	v_and_b32_e32 v203, 0xffff0000, v203
	v_pk_add_f32 v[62:63], v[62:63], v[202:203]
	v_pk_add_f32 v[60:61], v[60:61], v[172:173]
	v_lshlrev_b32_e32 v210, 16, v204
	v_and_b32_e32 v211, 0xffff0000, v204
	v_mul_f32_e32 v172, v61, v61
	v_mul_f32_e32 v173, v63, v63
	v_pk_add_f32 v[56:57], v[56:57], v[210:211]
	v_fmac_f32_e32 v172, v60, v60
	v_fmac_f32_e32 v173, v62, v62
	v_lshlrev_b32_e32 v204, 16, v205
	v_and_b32_e32 v205, 0xffff0000, v205
	v_add_f32_e32 v172, v172, v173
	v_mul_f32_e32 v173, v57, v57
	v_pk_add_f32 v[58:59], v[58:59], v[204:205]
	v_fmac_f32_e32 v173, v56, v56
	v_add_f32_e32 v172, v173, v172
	v_mul_f32_e32 v173, v59, v59
	v_fmac_f32_e32 v173, v58, v58
	v_add_f32_e32 v177, v173, v172
	s_waitcnt vmcnt(6)
	v_lshlrev_b32_e32 v172, 16, v206
	v_and_b32_e32 v173, 0xffff0000, v206
	v_lshlrev_b32_e32 v202, 16, v207
	v_and_b32_e32 v203, 0xffff0000, v207
	v_pk_add_f32 v[54:55], v[54:55], v[202:203]
	v_pk_add_f32 v[52:53], v[52:53], v[172:173]
	v_lshlrev_b32_e32 v204, 16, v208
	v_and_b32_e32 v205, 0xffff0000, v208
	v_mul_f32_e32 v172, v53, v53
	v_mul_f32_e32 v173, v55, v55
	v_pk_add_f32 v[48:49], v[48:49], v[204:205]
	v_fmac_f32_e32 v172, v52, v52
	v_fmac_f32_e32 v173, v54, v54
	v_lshlrev_b32_e32 v206, 16, v209
	v_and_b32_e32 v207, 0xffff0000, v209
	v_add_f32_e32 v172, v172, v173
	v_mul_f32_e32 v173, v49, v49
	v_pk_add_f32 v[50:51], v[50:51], v[206:207]
	v_fmac_f32_e32 v173, v48, v48
	v_add_f32_e32 v172, v173, v172
	v_mul_f32_e32 v173, v51, v51
	v_fmac_f32_e32 v173, v50, v50
	v_add_f32_e32 v172, v173, v172
	v_add_f32_e32 v172, v177, v172
	ds_bpermute_b32 v173, v175, v172
	s_waitcnt lgkmcnt(0)
	v_add_f32_e32 v172, v172, v173
	ds_bpermute_b32 v173, v176, v172
	s_and_saveexec_b64 s[14:15], s[0:1]
	s_cbranch_execz .LBB0_968
	s_waitcnt lgkmcnt(0)
	v_add_f32_e32 v172, v172, v173
	ds_write_b32 v201, v172 offset:2048

.LBB0_989:
	s_or_b64 exec, exec, s[12:13]
	v_lshlrev_b64 v[80:81], 2, v[170:171]
	s_waitcnt vmcnt(0) lgkmcnt(0)
	s_barrier
	v_lshl_add_u64 v[0:1], s[48:49], 0, v[80:81]
	global_load_dwordx4 v[12:15], v[0:1], off nt
	global_load_dwordx4 v[8:11], v[0:1], off offset:16 nt
	global_load_dwordx4 v[4:7], v[0:1], off offset:512 nt
	s_nop 0
	global_load_dwordx4 v[0:3], v[0:1], off offset:528 nt
	v_add_u32_e32 v84, s52, v182
	v_add_u32_e32 v174, s52, v183
	v_ashrrev_i32_e32 v85, 31, v84
	v_lshlrev_b64 v[82:83], 12, v[168:169]
	v_ashrrev_i32_e32 v175, 31, v174
	v_lshlrev_b64 v[84:85], 12, v[84:85]
	v_lshl_add_u64 v[176:177], s[50:51], 0, v[82:83]
	ds_read_b32 v170, v189
	ds_read_b32 v168, v190
	ds_read_b32 v82, v191
	ds_read_b32 v86, v192
	ds_read_b32 v172, v193
	ds_read_b32 v202, v194
	ds_read_b32 v204, v195
	ds_read_b32 v206, v196
	v_lshlrev_b64 v[174:175], 12, v[174:175]
	v_lshl_add_u64 v[84:85], s[50:51], 0, v[84:85]
	s_waitcnt lgkmcnt(7)
	v_pk_mul_f32 v[126:127], v[126:127], v[170:171] op_sel_hi:[1,0]
	v_pk_mul_f32 v[124:125], v[124:125], v[170:171] op_sel_hi:[1,0]
	v_lshl_add_u64 v[176:177], v[176:177], 0, v[80:81]
	v_lshl_add_u64 v[174:175], s[50:51], 0, v[174:175]
	v_lshl_add_u64 v[84:85], v[84:85], 0, v[80:81]
	v_pk_mul_f32 v[122:123], v[122:123], v[170:171] op_sel_hi:[1,0]
	v_pk_mul_f32 v[120:121], v[120:121], v[170:171] op_sel_hi:[1,0]
	v_pk_mul_f32 v[118:119], v[118:119], v[170:171] op_sel_hi:[1,0]
	v_pk_mul_f32 v[116:117], v[116:117], v[170:171] op_sel_hi:[1,0]
	v_pk_mul_f32 v[114:115], v[114:115], v[170:171] op_sel_hi:[1,0]
	v_pk_mul_f32 v[112:113], v[112:113], v[170:171] op_sel_hi:[1,0]
	s_waitcnt lgkmcnt(6)
	v_pk_mul_f32 v[110:111], v[110:111], v[168:169] op_sel_hi:[1,0]
	v_pk_mul_f32 v[170:171], v[108:109], v[168:169] op_sel_hi:[1,0]
	v_pk_mul_f32 v[208:209], v[106:107], v[168:169] op_sel_hi:[1,0]
	v_pk_mul_f32 v[210:211], v[104:105], v[168:169] op_sel_hi:[1,0]
	v_pk_mul_f32 v[212:213], v[102:103], v[168:169] op_sel_hi:[1,0]
	v_pk_mul_f32 v[216:217], v[100:101], v[168:169] op_sel_hi:[1,0]
	v_pk_mul_f32 v[218:219], v[98:99], v[168:169] op_sel_hi:[1,0]
	v_pk_mul_f32 v[168:169], v[96:97], v[168:169] op_sel_hi:[1,0]
	s_waitcnt lgkmcnt(5)
	v_pk_mul_f32 v[220:221], v[94:95], v[82:83] op_sel_hi:[1,0]
	v_pk_mul_f32 v[222:223], v[92:93], v[82:83] op_sel_hi:[1,0]
	v_pk_mul_f32 v[224:225], v[90:91], v[82:83] op_sel_hi:[1,0]
	v_pk_mul_f32 v[226:227], v[140:141], v[82:83] op_sel_hi:[1,0]
	v_pk_mul_f32 v[228:229], v[138:139], v[82:83] op_sel_hi:[1,0]
	v_pk_mul_f32 v[142:143], v[142:143], v[82:83] op_sel_hi:[1,0]
	v_lshl_add_u64 v[174:175], v[174:175], 0, v[80:81]
	s_waitcnt lgkmcnt(3)
	v_pk_mul_f32 v[50:51], v[50:51], v[172:173] op_sel_hi:[1,0]
	v_pk_mul_f32 v[48:49], v[48:49], v[172:173] op_sel_hi:[1,0]
	s_waitcnt lgkmcnt(2)
	v_pk_mul_f32 v[34:35], v[34:35], v[202:203] op_sel_hi:[1,0]
	v_pk_mul_f32 v[32:33], v[32:33], v[202:203] op_sel_hi:[1,0]
	s_waitcnt lgkmcnt(1)
	v_pk_mul_f32 v[18:19], v[18:19], v[204:205] op_sel_hi:[1,0]
	v_pk_mul_f32 v[16:17], v[16:17], v[204:205] op_sel_hi:[1,0]
	v_pk_mul_f32 v[22:23], v[22:23], v[204:205] op_sel_hi:[1,0]
	v_pk_mul_f32 v[20:21], v[20:21], v[204:205] op_sel_hi:[1,0]
	v_pk_mul_f32 v[62:63], v[62:63], v[172:173] op_sel_hi:[1,0]
	v_pk_mul_f32 v[60:61], v[60:61], v[172:173] op_sel_hi:[1,0]
	v_pk_mul_f32 v[46:47], v[46:47], v[202:203] op_sel_hi:[1,0]
	v_pk_mul_f32 v[44:45], v[44:45], v[202:203] op_sel_hi:[1,0]
	v_pk_mul_f32 v[30:31], v[30:31], v[204:205] op_sel_hi:[1,0]
	v_pk_mul_f32 v[28:29], v[28:29], v[204:205] op_sel_hi:[1,0]
	v_pk_mul_f32 v[58:59], v[58:59], v[172:173] op_sel_hi:[1,0]
	v_pk_mul_f32 v[56:57], v[56:57], v[172:173] op_sel_hi:[1,0]
	v_pk_mul_f32 v[42:43], v[42:43], v[202:203] op_sel_hi:[1,0]
	v_pk_mul_f32 v[40:41], v[40:41], v[202:203] op_sel_hi:[1,0]
	v_pk_mul_f32 v[26:27], v[26:27], v[204:205] op_sel_hi:[1,0]
	v_pk_mul_f32 v[24:25], v[24:25], v[204:205] op_sel_hi:[1,0]
	v_pk_mul_f32 v[54:55], v[54:55], v[172:173] op_sel_hi:[1,0]
	v_pk_mul_f32 v[52:53], v[52:53], v[172:173] op_sel_hi:[1,0]
	v_pk_mul_f32 v[38:39], v[38:39], v[202:203] op_sel_hi:[1,0]
	v_pk_mul_f32 v[36:37], v[36:37], v[202:203] op_sel_hi:[1,0]
	s_and_b64 vcc, exec, s[40:41]
	s_mov_b64 s[12:13], -1
	s_waitcnt vmcnt(3)
	v_pk_mul_f32 v[92:93], v[14:15], v[126:127]
	v_pk_mul_f32 v[90:91], v[12:13], v[124:125]
	s_waitcnt vmcnt(2)
	v_pk_mul_f32 v[96:97], v[10:11], v[122:123]
	v_pk_mul_f32 v[94:95], v[8:9], v[120:121]
	s_waitcnt vmcnt(1)
	v_pk_mul_f32 v[100:101], v[6:7], v[118:119]
	v_pk_mul_f32 v[98:99], v[4:5], v[116:117]
	s_waitcnt vmcnt(0)
	v_pk_mul_f32 v[104:105], v[2:3], v[114:115]
	v_pk_mul_f32 v[102:103], v[0:1], v[112:113]
	v_pk_mul_f32 v[108:109], v[14:15], v[110:111]
	v_pk_mul_f32 v[106:107], v[12:13], v[170:171]
	v_pk_mul_f32 v[112:113], v[10:11], v[208:209]
	v_pk_mul_f32 v[110:111], v[8:9], v[210:211]
	v_pk_mul_f32 v[116:117], v[6:7], v[212:213]
	v_pk_mul_f32 v[114:115], v[4:5], v[216:217]
	v_pk_mul_f32 v[120:121], v[2:3], v[218:219]
	v_pk_mul_f32 v[118:119], v[0:1], v[168:169]
	v_pk_mul_f32 v[124:125], v[14:15], v[220:221]
	v_pk_mul_f32 v[122:123], v[12:13], v[222:223]
	v_pk_mul_f32 v[140:141], v[10:11], v[224:225]
	v_pk_mul_f32 v[138:139], v[8:9], v[226:227]
	v_pk_mul_f32 v[170:171], v[6:7], v[228:229]
	v_pk_mul_f32 v[168:169], v[4:5], v[142:143]
	global_store_dwordx4 v[176:177], v[90:93], off
	global_store_dwordx4 v[176:177], v[94:97], off offset:16
	global_store_dwordx4 v[176:177], v[98:101], off offset:512
	global_store_dwordx4 v[176:177], v[102:105], off offset:528
	global_store_dwordx4 v[84:85], v[106:109], off
	global_store_dwordx4 v[84:85], v[110:113], off offset:16
	global_store_dwordx4 v[84:85], v[114:117], off offset:512
	global_store_dwordx4 v[84:85], v[118:121], off offset:528
	global_store_dwordx4 v[174:175], v[122:125], off
	global_store_dwordx4 v[174:175], v[138:141], off offset:16
	global_store_dwordx4 v[174:175], v[168:171], off offset:512
	v_pk_mul_f32 v[84:85], v[88:89], v[82:83] op_sel_hi:[1,0]
	v_pk_mul_f32 v[82:83], v[136:137], v[82:83] op_sel_hi:[1,0]
	v_pk_mul_f32 v[84:85], v[2:3], v[84:85]
	v_pk_mul_f32 v[82:83], v[0:1], v[82:83]
	global_store_dwordx4 v[174:175], v[82:85], off offset:528
	v_pk_mul_f32 v[90:91], v[134:135], v[86:87] op_sel_hi:[1,0]
	v_pk_mul_f32 v[50:51], v[2:3], v[50:51]
	v_add_u32_e32 v82, s52, v184
	v_ashrrev_i32_e32 v83, 31, v82
	v_lshlrev_b64 v[82:83], 12, v[82:83]
	v_lshl_add_u64 v[82:83], s[50:51], 0, v[82:83]
	v_lshl_add_u64 v[88:89], v[82:83], 0, v[80:81]
	v_pk_mul_f32 v[82:83], v[132:133], v[86:87] op_sel_hi:[1,0]
	v_pk_mul_f32 v[48:49], v[0:1], v[48:49]
	v_pk_mul_f32 v[84:85], v[14:15], v[82:83]
	v_pk_mul_f32 v[82:83], v[12:13], v[90:91]
	global_store_dwordx4 v[88:89], v[82:85], off
	v_pk_mul_f32 v[90:91], v[146:147], v[86:87] op_sel_hi:[1,0]
	v_pk_mul_f32 v[34:35], v[2:3], v[34:35]
	v_pk_mul_f32 v[82:83], v[144:145], v[86:87] op_sel_hi:[1,0]
	v_pk_mul_f32 v[32:33], v[0:1], v[32:33]
	v_pk_mul_f32 v[84:85], v[10:11], v[82:83]
	v_pk_mul_f32 v[82:83], v[8:9], v[90:91]
	global_store_dwordx4 v[88:89], v[82:85], off offset:16
	v_pk_mul_f32 v[90:91], v[130:131], v[86:87] op_sel_hi:[1,0]
	v_pk_mul_f32 v[18:19], v[2:3], v[18:19]
	v_pk_mul_f32 v[82:83], v[128:129], v[86:87] op_sel_hi:[1,0]
	v_pk_mul_f32 v[16:17], v[0:1], v[16:17]
	v_pk_mul_f32 v[84:85], v[6:7], v[82:83]
	v_pk_mul_f32 v[82:83], v[4:5], v[90:91]
	global_store_dwordx4 v[88:89], v[82:85], off offset:512
	v_pk_mul_f32 v[22:23], v[6:7], v[22:23]
	v_pk_mul_f32 v[20:21], v[4:5], v[20:21]
	v_pk_mul_f32 v[82:83], v[148:149], v[86:87] op_sel_hi:[1,0]
	v_pk_mul_f32 v[86:87], v[150:151], v[86:87] op_sel_hi:[1,0]
	v_pk_mul_f32 v[84:85], v[2:3], v[82:83]
	v_pk_mul_f32 v[82:83], v[0:1], v[86:87]
	global_store_dwordx4 v[88:89], v[82:85], off offset:528
	v_pk_mul_f32 v[62:63], v[14:15], v[62:63]
	v_pk_mul_f32 v[60:61], v[12:13], v[60:61]
	v_add_u32_e32 v82, s52, v185
	v_ashrrev_i32_e32 v83, 31, v82
	v_lshlrev_b64 v[82:83], 12, v[82:83]
	v_lshl_add_u64 v[82:83], s[50:51], 0, v[82:83]
	v_lshl_add_u64 v[82:83], v[82:83], 0, v[80:81]
	global_store_dwordx4 v[82:83], v[48:51], off offset:528
	v_pk_mul_f32 v[46:47], v[14:15], v[46:47]
	v_pk_mul_f32 v[44:45], v[12:13], v[44:45]
	v_add_u32_e32 v48, s52, v186
	v_ashrrev_i32_e32 v49, 31, v48
	v_lshlrev_b64 v[48:49], 12, v[48:49]
	v_lshl_add_u64 v[48:49], s[50:51], 0, v[48:49]
	v_lshl_add_u64 v[48:49], v[48:49], 0, v[80:81]
	global_store_dwordx4 v[48:49], v[32:35], off offset:528
	v_pk_mul_f32 v[30:31], v[14:15], v[30:31]
	v_pk_mul_f32 v[28:29], v[12:13], v[28:29]
	v_add_u32_e32 v32, s52, v187
	v_ashrrev_i32_e32 v33, 31, v32
	v_lshlrev_b64 v[32:33], 12, v[32:33]
	v_lshl_add_u64 v[32:33], s[50:51], 0, v[32:33]
	v_lshl_add_u64 v[32:33], v[32:33], 0, v[80:81]
	global_store_dwordx4 v[32:33], v[16:19], off offset:528
	global_store_dwordx4 v[32:33], v[20:23], off offset:512
	v_pk_mul_f32 v[58:59], v[10:11], v[58:59]
	v_add_u32_e32 v16, s52, v188
	v_ashrrev_i32_e32 v17, 31, v16
	v_lshlrev_b64 v[16:17], 12, v[16:17]
	v_lshl_add_u64 v[16:17], s[50:51], 0, v[16:17]
	s_waitcnt lgkmcnt(0)
	v_pk_mul_f32 v[18:19], v[72:73], v[206:207] op_sel_hi:[1,0]
	v_pk_mul_f32 v[20:21], v[74:75], v[206:207] op_sel_hi:[1,0]
	v_lshl_add_u64 v[16:17], v[16:17], 0, v[80:81]
	v_pk_mul_f32 v[14:15], v[14:15], v[18:19]
	v_pk_mul_f32 v[12:13], v[12:13], v[20:21]
	global_store_dwordx4 v[16:17], v[12:15], off
	v_pk_mul_f32 v[56:57], v[8:9], v[56:57]
	v_pk_mul_f32 v[42:43], v[10:11], v[42:43]
	v_pk_mul_f32 v[12:13], v[68:69], v[206:207] op_sel_hi:[1,0]
	v_pk_mul_f32 v[14:15], v[70:71], v[206:207] op_sel_hi:[1,0]
	v_pk_mul_f32 v[40:41], v[8:9], v[40:41]
	v_pk_mul_f32 v[26:27], v[10:11], v[26:27]
	v_pk_mul_f32 v[24:25], v[8:9], v[24:25]
	v_pk_mul_f32 v[10:11], v[10:11], v[12:13]
	v_pk_mul_f32 v[8:9], v[8:9], v[14:15]
	global_store_dwordx4 v[16:17], v[8:11], off offset:16
	v_pk_mul_f32 v[54:55], v[6:7], v[54:55]
	v_pk_mul_f32 v[52:53], v[4:5], v[52:53]
	v_pk_mul_f32 v[8:9], v[76:77], v[206:207] op_sel_hi:[1,0]
	v_pk_mul_f32 v[10:11], v[78:79], v[206:207] op_sel_hi:[1,0]
	v_pk_mul_f32 v[38:39], v[6:7], v[38:39]
	v_pk_mul_f32 v[36:37], v[4:5], v[36:37]
	v_pk_mul_f32 v[6:7], v[6:7], v[8:9]
	v_pk_mul_f32 v[4:5], v[4:5], v[10:11]
	global_store_dwordx4 v[16:17], v[4:7], off offset:512
	global_store_dwordx4 v[82:83], v[60:63], off
	global_store_dwordx4 v[82:83], v[56:59], off offset:16
	v_pk_mul_f32 v[4:5], v[64:65], v[206:207] op_sel_hi:[1,0]
	v_pk_mul_f32 v[6:7], v[66:67], v[206:207] op_sel_hi:[1,0]
	v_pk_mul_f32 v[2:3], v[2:3], v[4:5]
	v_pk_mul_f32 v[0:1], v[0:1], v[6:7]
	global_store_dwordx4 v[82:83], v[52:55], off offset:512
	global_store_dwordx4 v[48:49], v[44:47], off
	global_store_dwordx4 v[48:49], v[40:43], off offset:16
	global_store_dwordx4 v[48:49], v[36:39], off offset:512
	global_store_dwordx4 v[32:33], v[28:31], off
	global_store_dwordx4 v[32:33], v[24:27], off offset:16
	global_store_dwordx4 v[16:17], v[0:3], off offset:528
	s_cbranch_vccnz .LBB0_943
	s_andn2_b64 vcc, exec, s[2:3]
	s_cbranch_vccnz .LBB0_942
	s_barrier
	s_branch .LBB0_942
